# split scan/attention, the two workgroups of a (batch, head) pair placed on the same XCD
# speedup vs baseline: 1.0177x; 1.0086x over previous
; __device__ __forceinline__ int obid() { int b = blockIdx.x; asm volatile("" : "+s"(b)); return b; }
; __device__ __forceinline__ void phase_scan2(const Params& p, int l, LAS unsigned char* lds) {
;     ...
;     for (int job = obid(); job < 256; job += gridDim.x) {
;         const int bh = job >> 2, rg = job & 3, b = bh >> 3, h = bh & 7;
;         const size_t tok0 = (size_t)b * SEQ;
;         const int pw = wid - 3, j = lane;
.Lsc_job:
	s_lshr_b32 s0, s13, 4
	s_lshl_b32 s0, s0, 3
	s_and_b32 s53, s13, 7
	s_add_u32 s0, s0, s53
	s_bfe_u32 s53, s13, 0x10003
	s_lshl_b32 s53, s53, 1
	s_lshr_b32 s54, s0, 3
	s_and_b32 s52, s0, 7
	s_cmp_eq_u32 s25, 0
	s_cbranch_scc1 .Lsc_consumer
	s_cmp_eq_u32 s25, 4
	s_cbranch_scc1 .Lsc_consumer

; __device__ __forceinline__ void phase_scan2(const Params& p, int l, LAS unsigned char* lds) {
;     ...
;         auto consume = [&](int c, LAS const unsigned char* sl) {
;             const bf16x8 s0 = __builtin_bit_cast(bf16x8, (u32x4){pk_bf16(ST[0][0], ST[0][1]), pk_bf16(ST[0][2], ST[0][3]), pk_bf16(ST[1][0], ST[1][1]), pk_bf16(ST[1][2], ST[1][3])});
;             const bf16x8 s1 = __builtin_bit_cast(bf16x8, (u32x4){pk_bf16(ST[2][0], ST[2][1]), pk_bf16(ST[2][2], ST[2][3]), pk_bf16(ST[3][0], ST[3][1]), pk_bf16(ST[3][2], ST[3][3])});
;             const bf16x8 at0 = *(LAS const bf16x8*)(sl + SC_AT + (fr * 32 + fq * 8) * 2), at1 = *(LAS const bf16x8*)(sl + SC_AT + ((16 + fr) * 32 + fq * 8) * 2);
;             const bf16x8 rt0 = *(LAS const bf16x8*)(sl + SC_RT + (fr * 32 + fq * 8) * 2), rt1 = *(LAS const bf16x8*)(sl + SC_RT + ((16 + fr) * 32 + fq * 8) * 2);
;             const int mo = (fr * 16 + 4 * fq) * 2;
;             const bf16x8 vf = frag4(sl + SC_VP + mo), akf = frag4(sl + SC_AK + mo), xf = frag4(sl + SC_X + mo), rbf = frag4(sl + SC_RB + mo), rkf = frag4(sl + SC_RK + mo);
;             const f32x4 z = (f32x4){0.f, 0.f, 0.f, 0.f};
;             f32x4 g = __builtin_amdgcn_mfma_f32_16x16x32_bf16(at0, s0, z, 0, 0, 0);
;             g = __builtin_amdgcn_mfma_f32_16x16x32_bf16(at1, s1, g, 0, 0, 0);
;             g = __builtin_amdgcn_mfma_f32_16x16x32_bf16(akf, vf, g, 0, 0, 0);
;             const f32x4 sa = __builtin_amdgcn_mfma_f32_16x16x32_bf16(xf, cfrag(g), z, 0, 0, 0);
;             const bf16x8 saf = cfrag(sa);
;             f32x4 y = __builtin_amdgcn_mfma_f32_16x16x32_bf16(rt0, s0, z, 0, 0, 0);
;             y = __builtin_amdgcn_mfma_f32_16x16x32_bf16(rt1, s1, y, 0, 0, 0);
;             y = __builtin_amdgcn_mfma_f32_16x16x32_bf16(rbf, saf, y, 0, 0, 0);
;             y = __builtin_amdgcn_mfma_f32_16x16x32_bf16(rkf, vf, y, 0, 0, 0);
; #pragma unroll
;             for (int jt = 0; jt < 4; ++jt) {
;                 const f32x4 wc = *(LAS const f32x4*)(sl + SC_WC + (16 * jt + 4 * fq) * 4);
;                 const bf16x8 bb = frag4(sl + SC_BBT + ((16 * jt + fr) * SC_BS + 4 * fq) * 2), kb = frag4(sl + SC_KBT + ((16 * jt + fr) * SC_BS + 4 * fq) * 2);
;                 f32x4 acc = ST[jt];
;                 acc = __builtin_amdgcn_mfma_f32_16x16x32_bf16(bb, saf, acc, 0, 0, 0);
;                 acc = __builtin_amdgcn_mfma_f32_16x16x32_bf16(kb, vf, acc, 0, 0, 0);
.Lsc_consumer:
	s_setprio 3
	v_and_b32_e32 v4, 7, v1
	s_lshr_b32 s1, s25, 2
	v_xor_b32_e32 v4, v4, v2
	s_mul_i32 s0, s1, 768
	v_lshlrev_b32_e32 v4, 4, v4
	v_and_b32_e32 v5, 3, v1
	v_lshl_add_u32 v159, v1, 7, v4
	v_lshrrev_b32_e32 v4, 2, v1
	v_add_u32_e32 v13, s0, v6
	v_lshl_add_u32 v4, v2, 2, v4
	s_add_u32 s53, s53, s1
	v_and_b32_e32 v161, 7, v4
	s_mul_i32 s0, s54, 4096
	v_xor_b32_e32 v161, v161, v5
	s_lshl_b32 s0, s0, 10
	v_lshlrev_b32_e32 v161, 4, v161
	s_lshl_b32 s14, s52, 7
	v_lshl_add_u32 v161, v4, 7, v161
	s_lshl_b32 s15, s53, 5
	s_add_u32 s0, s0, s14
	v_lshlrev_b32_e32 v160, 5, v2
	v_add_u32_e32 v161, 4096, v161
	v_lshlrev_b32_e32 v162, 12, v2
	s_add_u32 s0, s0, s15
	s_add_u32 s0, s0, 0x5000000
	v_mov_b32_e32 v8, 0
	v_mov_b32_e32 v116, 0
	v_mov_b32_e32 v9, 0
	v_mov_b32_e32 v117, 0
	v_mov_b32_e32 v10, 0
	v_mov_b32_e32 v118, 0
	v_mov_b32_e32 v11, 0
	v_mov_b32_e32 v119, 0
	v_mov_b32_e32 v16, 0
	v_mov_b32_e32 v120, 0
	v_mov_b32_e32 v17, 0
	v_mov_b32_e32 v121, 0
	v_mov_b32_e32 v18, 0
	v_mov_b32_e32 v122, 0
	v_mov_b32_e32 v19, 0
	v_mov_b32_e32 v123, 0
	v_mov_b32_e32 v20, 0
	v_mov_b32_e32 v124, 0
	v_mov_b32_e32 v21, 0
	v_mov_b32_e32 v125, 0
	v_mov_b32_e32 v22, 0
	v_mov_b32_e32 v126, 0
	v_mov_b32_e32 v23, 0
	v_mov_b32_e32 v127, 0
	v_mov_b32_e32 v24, 0
	v_mov_b32_e32 v128, 0
	v_mov_b32_e32 v25, 0
	v_mov_b32_e32 v129, 0
	v_mov_b32_e32 v26, 0
	v_mov_b32_e32 v130, 0
	v_mov_b32_e32 v27, 0
	v_mov_b32_e32 v131, 0
	v_xor_b32_e32 v165, 64, v159
	v_add_u32_e32 v160, 10752, v160
	v_xor_b32_e32 v166, 64, v161
	v_lshl_add_u32 v162, v1, 1, v162
	s_add_u32 s48, s74, s0
	s_addc_u32 s49, s75, 0
	s_mov_b32 s42, 0
	s_mov_b32 s58, 0
	s_mov_b32 s56, 0
	s_branch .Lsc_c_bar
.Lsc_c_loop:
	s_mov_b32 s57, s56
	s_cmp_ge_u32 s58, 256
	s_cbranch_scc1 .Lsc_c_itend
	v_add_u32_e32 v82, s57, v159
	v_add_u32_e32 v167, s57, v165
	ds_read_b128 v[36:39], v82 offset:0
	ds_read_b128 v[44:47], v82 offset:2048
	v_add_u32_e32 v156, s57, v13
	ds_read_b128 v[40:43], v167 offset:0
	v_add_u32_e32 v164, s57, v7
	ds_read_b128 v[48:51], v167 offset:2048
	ds_read_b64 v[60:61], v156 offset:10240
	ds_read_b64_tr_b16 v[14:15], v164 offset:8192
	ds_read_b64_tr_b16 v[52:53], v164 offset:8704
	v_add_u32_e32 v158, s57, v161
	ds_read_b64_tr_b16 v[56:57], v164 offset:9728
	ds_read_b64_tr_b16 v[58:59], v164 offset:9216
	v_add_u32_e32 v168, s57, v166
	ds_read_b64_tr_b16 v[88:89], v158 offset:2048
	ds_read_b64_tr_b16 v[92:93], v158 offset:2056
	v_add_u32_e32 v157, s57, v160
	ds_read_b64_tr_b16 v[96:97], v168 offset:2048
	v_cvt_pk_bf16_f32 v28, v8, v9
	v_cvt_pk_bf16_f32 v29, v10, v11
	v_cvt_pk_bf16_f32 v30, v16, v17
	v_cvt_pk_bf16_f32 v31, v18, v19
	v_cvt_pk_bf16_f32 v32, v20, v21
	v_cvt_pk_bf16_f32 v33, v22, v23
	v_cvt_pk_bf16_f32 v34, v24, v25
	v_cvt_pk_bf16_f32 v35, v26, v27
	ds_read_b64_tr_b16 v[100:101], v168 offset:2056
	s_waitcnt lgkmcnt(12)
	v_mfma_f32_16x16x32_bf16 v[104:107], v[36:39], v[28:31], 0
	ds_read_b128 v[36:39], v82 offset:11520
	s_waitcnt lgkmcnt(12)
	v_mfma_f32_16x16x32_bf16 v[112:115], v[44:47], v[28:31], 0
	ds_read_b128 v[44:47], v82 offset:13568
	s_waitcnt lgkmcnt(12)
	v_mfma_f32_16x16x32_bf16 v[104:107], v[40:43], v[32:35], v[104:107]
	ds_read_b128 v[40:43], v167 offset:11520
	s_waitcnt lgkmcnt(12)
	v_mfma_f32_16x16x32_bf16 v[112:115], v[48:51], v[32:35], v[112:115]
	ds_read_b128 v[48:51], v167 offset:13568
	s_waitcnt lgkmcnt(11)
	s_nop 0
	v_mfma_f32_16x16x16_bf16 v[104:107], v[14:15], v[60:61], v[104:107]
	ds_read_b64_tr_b16 v[90:91], v158 offset:0
	ds_read_b64_tr_b16 v[94:95], v158 offset:8
	ds_read_b64_tr_b16 v[98:99], v168 offset:0
	ds_read_b64_tr_b16 v[102:103], v168 offset:8
	s_nop 3
	v_cvt_pk_bf16_f32 v54, v104, v105
	v_cvt_pk_bf16_f32 v55, v106, v107
	s_waitcnt lgkmcnt(14)
	s_nop 0
	v_mfma_f32_16x16x16_bf16 v[108:111], v[52:53], v[54:55], 0
	s_nop 7
	v_cvt_pk_bf16_f32 v62, v108, v109
	v_cvt_pk_bf16_f32 v63, v110, v111
	s_waitcnt lgkmcnt(0)
	s_nop 0
	v_mfma_f32_16x16x32_bf16 v[112:115], v[56:59], v[60:63], v[112:115]
	v_mfma_f32_16x16x32_bf16 v[8:11], v[88:91], v[60:63], v[8:11]
	v_mfma_f32_16x16x32_bf16 v[16:19], v[92:95], v[60:63], v[16:19]
	v_mfma_f32_16x16x32_bf16 v[20:23], v[96:99], v[60:63], v[20:23]
	v_mfma_f32_16x16x32_bf16 v[24:27], v[100:103], v[60:63], v[24:27]
	ds_read_b128 v[64:67], v157 offset:0
	ds_read_b128 v[68:71], v157 offset:16
	ds_read_b128 v[72:75], v157 offset:128
	ds_read_b128 v[84:87], v157 offset:144
	v_cvt_pk_bf16_f32 v163, v112, v112
	ds_read_b64 v[60:61], v156 offset:21760
	global_store_short v162, v163, s[48:49] offset:0
	v_cvt_pk_bf16_f32 v163, v113, v113
	global_store_short v162, v163, s[48:49] offset:1024
	v_cvt_pk_bf16_f32 v163, v114, v114
	global_store_short v162, v163, s[48:49] offset:2048
	v_cvt_pk_bf16_f32 v163, v115, v115
	global_store_short v162, v163, s[48:49] offset:3072
	s_waitcnt lgkmcnt(1)
	s_add_u32 s58, s58, 1
	s_add_u32 s48, s48, 0x4000
	s_addc_u32 s49, s49, 0
	v_pk_mul_f32 v[8:9], v[8:9], v[64:65]
	v_pk_mul_f32 v[10:11], v[10:11], v[66:67]
	v_pk_mul_f32 v[16:17], v[16:17], v[68:69]
	v_pk_mul_f32 v[18:19], v[18:19], v[70:71]
	v_pk_mul_f32 v[20:21], v[20:21], v[72:73]
	v_pk_mul_f32 v[22:23], v[22:23], v[74:75]
	v_pk_mul_f32 v[24:25], v[24:25], v[84:85]
	v_pk_mul_f32 v[26:27], v[26:27], v[86:87]
	s_add_u32 s57, s57, 11520
	s_cmp_ge_u32 s58, 256
	s_cbranch_scc1 .Lsc_c_itend
; __device__ __forceinline__ void phase_scan2(const Params& p, int l, LAS unsigned char* lds) {
;     ...
;         auto consume = [&](int c, LAS const unsigned char* sl) {
;             const bf16x8 s0 = __builtin_bit_cast(bf16x8, (u32x4){pk_bf16(ST[0][0], ST[0][1]), pk_bf16(ST[0][2], ST[0][3]), pk_bf16(ST[1][0], ST[1][1]), pk_bf16(ST[1][2], ST[1][3])});
;             const bf16x8 s1 = __builtin_bit_cast(bf16x8, (u32x4){pk_bf16(ST[2][0], ST[2][1]), pk_bf16(ST[2][2], ST[2][3]), pk_bf16(ST[3][0], ST[3][1]), pk_bf16(ST[3][2], ST[3][3])});
;             const bf16x8 at0 = *(LAS const bf16x8*)(sl + SC_AT + (fr * 32 + fq * 8) * 2), at1 = *(LAS const bf16x8*)(sl + SC_AT + ((16 + fr) * 32 + fq * 8) * 2);
;             const bf16x8 rt0 = *(LAS const bf16x8*)(sl + SC_RT + (fr * 32 + fq * 8) * 2), rt1 = *(LAS const bf16x8*)(sl + SC_RT + ((16 + fr) * 32 + fq * 8) * 2);
;             const int mo = (fr * 16 + 4 * fq) * 2;
;             const bf16x8 vf = frag4(sl + SC_VP + mo), akf = frag4(sl + SC_AK + mo), xf = frag4(sl + SC_X + mo), rbf = frag4(sl + SC_RB + mo), rkf = frag4(sl + SC_RK + mo);
;             const f32x4 z = (f32x4){0.f, 0.f, 0.f, 0.f};
;             f32x4 g = __builtin_amdgcn_mfma_f32_16x16x32_bf16(at0, s0, z, 0, 0, 0);
;             g = __builtin_amdgcn_mfma_f32_16x16x32_bf16(at1, s1, g, 0, 0, 0);
;             g = __builtin_amdgcn_mfma_f32_16x16x32_bf16(akf, vf, g, 0, 0, 0);
;             const f32x4 sa = __builtin_amdgcn_mfma_f32_16x16x32_bf16(xf, cfrag(g), z, 0, 0, 0);
;             const bf16x8 saf = cfrag(sa);
;             f32x4 y = __builtin_amdgcn_mfma_f32_16x16x32_bf16(rt0, s0, z, 0, 0, 0);
;             y = __builtin_amdgcn_mfma_f32_16x16x32_bf16(rt1, s1, y, 0, 0, 0);
;             y = __builtin_amdgcn_mfma_f32_16x16x32_bf16(rbf, saf, y, 0, 0, 0);
;             y = __builtin_amdgcn_mfma_f32_16x16x32_bf16(rkf, vf, y, 0, 0, 0);
; #pragma unroll
;             for (int jt = 0; jt < 4; ++jt) {
;                 const f32x4 wc = *(LAS const f32x4*)(sl + SC_WC + (16 * jt + 4 * fq) * 4);
;                 const bf16x8 bb = frag4(sl + SC_BBT + ((16 * jt + fr) * SC_BS + 4 * fq) * 2), kb = frag4(sl + SC_KBT + ((16 * jt + fr) * SC_BS + 4 * fq) * 2);
;                 f32x4 acc = ST[jt];
;                 acc = __builtin_amdgcn_mfma_f32_16x16x32_bf16(bb, saf, acc, 0, 0, 0);
;                 acc = __builtin_amdgcn_mfma_f32_16x16x32_bf16(kb, vf, acc, 0, 0, 0);
	v_add_u32_e32 v164, s57, v7
	v_add_u32_e32 v158, s57, v161
	ds_read_b64_tr_b16 v[14:15], v164 offset:8192
	ds_read_b64_tr_b16 v[52:53], v164 offset:8704
	ds_read_b64_tr_b16 v[56:57], v164 offset:9728
	ds_read_b64_tr_b16 v[58:59], v164 offset:9216
	v_add_u32_e32 v168, s57, v166
	ds_read_b64_tr_b16 v[88:89], v158 offset:2048
	ds_read_b64_tr_b16 v[92:93], v158 offset:2056
	v_add_u32_e32 v82, s57, v159
	v_add_u32_e32 v156, s57, v13
	v_add_u32_e32 v157, s57, v160
	v_add_u32_e32 v167, s57, v165
	ds_read_b64_tr_b16 v[96:97], v168 offset:2048
	v_cvt_pk_bf16_f32 v28, v8, v9
	v_cvt_pk_bf16_f32 v29, v10, v11
	v_cvt_pk_bf16_f32 v30, v16, v17
	v_cvt_pk_bf16_f32 v31, v18, v19
	v_cvt_pk_bf16_f32 v32, v20, v21
	v_cvt_pk_bf16_f32 v33, v22, v23
	v_cvt_pk_bf16_f32 v34, v24, v25
	v_cvt_pk_bf16_f32 v35, v26, v27
	ds_read_b64_tr_b16 v[100:101], v168 offset:2056
	s_waitcnt lgkmcnt(12)
	v_mfma_f32_16x16x32_bf16 v[104:107], v[36:39], v[28:31], 0
	ds_read_b128 v[36:39], v82 offset:11520
	s_waitcnt lgkmcnt(12)
	v_mfma_f32_16x16x32_bf16 v[112:115], v[44:47], v[28:31], 0
	ds_read_b128 v[44:47], v82 offset:13568
	s_waitcnt lgkmcnt(12)
	v_mfma_f32_16x16x32_bf16 v[104:107], v[40:43], v[32:35], v[104:107]
	ds_read_b128 v[40:43], v167 offset:11520
	s_waitcnt lgkmcnt(12)
	v_mfma_f32_16x16x32_bf16 v[112:115], v[48:51], v[32:35], v[112:115]
	ds_read_b128 v[48:51], v167 offset:13568
	s_waitcnt lgkmcnt(11)
	s_nop 0
	v_mfma_f32_16x16x16_bf16 v[104:107], v[14:15], v[60:61], v[104:107]
	ds_read_b64_tr_b16 v[90:91], v158 offset:0
	ds_read_b64_tr_b16 v[94:95], v158 offset:8
	ds_read_b64_tr_b16 v[98:99], v168 offset:0
	ds_read_b64_tr_b16 v[102:103], v168 offset:8
	s_nop 3
	v_cvt_pk_bf16_f32 v54, v104, v105
	v_cvt_pk_bf16_f32 v55, v106, v107
	s_waitcnt lgkmcnt(14)
	s_nop 0
	v_mfma_f32_16x16x16_bf16 v[108:111], v[52:53], v[54:55], 0
	s_nop 7
	v_cvt_pk_bf16_f32 v62, v108, v109
	v_cvt_pk_bf16_f32 v63, v110, v111
	s_waitcnt lgkmcnt(0)
	s_nop 0
	v_mfma_f32_16x16x32_bf16 v[112:115], v[56:59], v[60:63], v[112:115]
	v_mfma_f32_16x16x32_bf16 v[8:11], v[88:91], v[60:63], v[8:11]
	v_mfma_f32_16x16x32_bf16 v[16:19], v[92:95], v[60:63], v[16:19]
	v_mfma_f32_16x16x32_bf16 v[20:23], v[96:99], v[60:63], v[20:23]
	v_mfma_f32_16x16x32_bf16 v[24:27], v[100:103], v[60:63], v[24:27]
	ds_read_b128 v[64:67], v157 offset:0
	ds_read_b128 v[68:71], v157 offset:16
	ds_read_b128 v[72:75], v157 offset:128
	ds_read_b128 v[84:87], v157 offset:144
	v_cvt_pk_bf16_f32 v163, v112, v112
	ds_read_b64 v[60:61], v156 offset:21760
	global_store_short v162, v163, s[48:49] offset:0
	v_cvt_pk_bf16_f32 v163, v113, v113
	global_store_short v162, v163, s[48:49] offset:1024
	v_cvt_pk_bf16_f32 v163, v114, v114
	global_store_short v162, v163, s[48:49] offset:2048
	v_cvt_pk_bf16_f32 v163, v115, v115
	global_store_short v162, v163, s[48:49] offset:3072
	s_waitcnt lgkmcnt(1)
	s_add_u32 s58, s58, 1
	s_add_u32 s48, s48, 0x4000
	s_addc_u32 s49, s49, 0
	v_pk_mul_f32 v[8:9], v[8:9], v[64:65]
	v_pk_mul_f32 v[10:11], v[10:11], v[66:67]
	v_pk_mul_f32 v[16:17], v[16:17], v[68:69]
	v_pk_mul_f32 v[18:19], v[18:19], v[70:71]
	v_pk_mul_f32 v[20:21], v[20:21], v[72:73]
	v_pk_mul_f32 v[22:23], v[22:23], v[74:75]
	v_pk_mul_f32 v[24:25], v[24:25], v[84:85]
	v_pk_mul_f32 v[26:27], v[26:27], v[86:87]
	s_add_u32 s57, s57, 11520
	s_cmp_ge_u32 s58, 256
	s_cbranch_scc1 .Lsc_c_itend
	v_add_u32_e32 v164, s57, v7
	v_add_u32_e32 v158, s57, v161
	ds_read_b64_tr_b16 v[14:15], v164 offset:8192
	ds_read_b64_tr_b16 v[52:53], v164 offset:8704
	ds_read_b64_tr_b16 v[56:57], v164 offset:9728
	ds_read_b64_tr_b16 v[58:59], v164 offset:9216
	v_add_u32_e32 v168, s57, v166
	ds_read_b64_tr_b16 v[88:89], v158 offset:2048
	ds_read_b64_tr_b16 v[92:93], v158 offset:2056
	v_add_u32_e32 v82, s57, v159
	v_add_u32_e32 v156, s57, v13
	v_add_u32_e32 v157, s57, v160
	v_add_u32_e32 v167, s57, v165
	ds_read_b64_tr_b16 v[96:97], v168 offset:2048
	v_cvt_pk_bf16_f32 v28, v8, v9
	v_cvt_pk_bf16_f32 v29, v10, v11
	v_cvt_pk_bf16_f32 v30, v16, v17
	v_cvt_pk_bf16_f32 v31, v18, v19
	v_cvt_pk_bf16_f32 v32, v20, v21
	v_cvt_pk_bf16_f32 v33, v22, v23
	v_cvt_pk_bf16_f32 v34, v24, v25
	v_cvt_pk_bf16_f32 v35, v26, v27
	ds_read_b64_tr_b16 v[100:101], v168 offset:2056
	s_waitcnt lgkmcnt(12)
	v_mfma_f32_16x16x32_bf16 v[104:107], v[36:39], v[28:31], 0
	ds_read_b128 v[36:39], v82 offset:11520
	s_waitcnt lgkmcnt(12)
	v_mfma_f32_16x16x32_bf16 v[112:115], v[44:47], v[28:31], 0
	ds_read_b128 v[44:47], v82 offset:13568
	s_waitcnt lgkmcnt(12)
	v_mfma_f32_16x16x32_bf16 v[104:107], v[40:43], v[32:35], v[104:107]
	ds_read_b128 v[40:43], v167 offset:11520
	s_waitcnt lgkmcnt(12)
	v_mfma_f32_16x16x32_bf16 v[112:115], v[48:51], v[32:35], v[112:115]
	ds_read_b128 v[48:51], v167 offset:13568
	s_waitcnt lgkmcnt(11)
	s_nop 0
	v_mfma_f32_16x16x16_bf16 v[104:107], v[14:15], v[60:61], v[104:107]
	ds_read_b64_tr_b16 v[90:91], v158 offset:0
	ds_read_b64_tr_b16 v[94:95], v158 offset:8
	ds_read_b64_tr_b16 v[98:99], v168 offset:0
	ds_read_b64_tr_b16 v[102:103], v168 offset:8
	s_nop 3
	v_cvt_pk_bf16_f32 v54, v104, v105
	v_cvt_pk_bf16_f32 v55, v106, v107
	s_waitcnt lgkmcnt(14)
	s_nop 0
	v_mfma_f32_16x16x16_bf16 v[108:111], v[52:53], v[54:55], 0
	s_nop 7
	v_cvt_pk_bf16_f32 v62, v108, v109
	v_cvt_pk_bf16_f32 v63, v110, v111
	s_waitcnt lgkmcnt(0)
	s_nop 0
	v_mfma_f32_16x16x32_bf16 v[112:115], v[56:59], v[60:63], v[112:115]
	v_mfma_f32_16x16x32_bf16 v[8:11], v[88:91], v[60:63], v[8:11]
	v_mfma_f32_16x16x32_bf16 v[16:19], v[92:95], v[60:63], v[16:19]
	v_mfma_f32_16x16x32_bf16 v[20:23], v[96:99], v[60:63], v[20:23]
	v_mfma_f32_16x16x32_bf16 v[24:27], v[100:103], v[60:63], v[24:27]
	ds_read_b128 v[64:67], v157 offset:0
	ds_read_b128 v[68:71], v157 offset:16
	ds_read_b128 v[72:75], v157 offset:128
	ds_read_b128 v[84:87], v157 offset:144
	v_cvt_pk_bf16_f32 v163, v112, v112
	ds_read_b64 v[60:61], v156 offset:21760
	global_store_short v162, v163, s[48:49] offset:0
	v_cvt_pk_bf16_f32 v163, v113, v113
	global_store_short v162, v163, s[48:49] offset:1024
	v_cvt_pk_bf16_f32 v163, v114, v114
	global_store_short v162, v163, s[48:49] offset:2048
	v_cvt_pk_bf16_f32 v163, v115, v115
	global_store_short v162, v163, s[48:49] offset:3072
	s_waitcnt lgkmcnt(1)
	s_add_u32 s58, s58, 1
	s_add_u32 s48, s48, 0x4000
	s_addc_u32 s49, s49, 0
	v_pk_mul_f32 v[8:9], v[8:9], v[64:65]
	v_pk_mul_f32 v[10:11], v[10:11], v[66:67]
	v_pk_mul_f32 v[16:17], v[16:17], v[68:69]
	v_pk_mul_f32 v[18:19], v[18:19], v[70:71]
	v_pk_mul_f32 v[20:21], v[20:21], v[72:73]
	v_pk_mul_f32 v[22:23], v[22:23], v[74:75]
	v_pk_mul_f32 v[24:25], v[24:25], v[84:85]
	v_pk_mul_f32 v[26:27], v[26:27], v[86:87]
	s_add_u32 s57, s57, 11520
	s_cmp_ge_u32 s58, 256
	s_cbranch_scc1 .Lsc_c_itend
; __device__ __forceinline__ void phase_scan2(const Params& p, int l, LAS unsigned char* lds) {
;     ...
;         auto consume = [&](int c, LAS const unsigned char* sl) {
;             const bf16x8 s0 = __builtin_bit_cast(bf16x8, (u32x4){pk_bf16(ST[0][0], ST[0][1]), pk_bf16(ST[0][2], ST[0][3]), pk_bf16(ST[1][0], ST[1][1]), pk_bf16(ST[1][2], ST[1][3])});
;             const bf16x8 s1 = __builtin_bit_cast(bf16x8, (u32x4){pk_bf16(ST[2][0], ST[2][1]), pk_bf16(ST[2][2], ST[2][3]), pk_bf16(ST[3][0], ST[3][1]), pk_bf16(ST[3][2], ST[3][3])});
;             const bf16x8 at0 = *(LAS const bf16x8*)(sl + SC_AT + (fr * 32 + fq * 8) * 2), at1 = *(LAS const bf16x8*)(sl + SC_AT + ((16 + fr) * 32 + fq * 8) * 2);
;             const bf16x8 rt0 = *(LAS const bf16x8*)(sl + SC_RT + (fr * 32 + fq * 8) * 2), rt1 = *(LAS const bf16x8*)(sl + SC_RT + ((16 + fr) * 32 + fq * 8) * 2);
;             const int mo = (fr * 16 + 4 * fq) * 2;
;             const bf16x8 vf = frag4(sl + SC_VP + mo), akf = frag4(sl + SC_AK + mo), xf = frag4(sl + SC_X + mo), rbf = frag4(sl + SC_RB + mo), rkf = frag4(sl + SC_RK + mo);
;             const f32x4 z = (f32x4){0.f, 0.f, 0.f, 0.f};
;             f32x4 g = __builtin_amdgcn_mfma_f32_16x16x32_bf16(at0, s0, z, 0, 0, 0);
;             g = __builtin_amdgcn_mfma_f32_16x16x32_bf16(at1, s1, g, 0, 0, 0);
;             g = __builtin_amdgcn_mfma_f32_16x16x32_bf16(akf, vf, g, 0, 0, 0);
;             const f32x4 sa = __builtin_amdgcn_mfma_f32_16x16x32_bf16(xf, cfrag(g), z, 0, 0, 0);
;             const bf16x8 saf = cfrag(sa);
;             f32x4 y = __builtin_amdgcn_mfma_f32_16x16x32_bf16(rt0, s0, z, 0, 0, 0);
;             y = __builtin_amdgcn_mfma_f32_16x16x32_bf16(rt1, s1, y, 0, 0, 0);
;             y = __builtin_amdgcn_mfma_f32_16x16x32_bf16(rbf, saf, y, 0, 0, 0);
;             y = __builtin_amdgcn_mfma_f32_16x16x32_bf16(rkf, vf, y, 0, 0, 0);
; #pragma unroll
;             for (int jt = 0; jt < 4; ++jt) {
;                 const f32x4 wc = *(LAS const f32x4*)(sl + SC_WC + (16 * jt + 4 * fq) * 4);
;                 const bf16x8 bb = frag4(sl + SC_BBT + ((16 * jt + fr) * SC_BS + 4 * fq) * 2), kb = frag4(sl + SC_KBT + ((16 * jt + fr) * SC_BS + 4 * fq) * 2);
;                 f32x4 acc = ST[jt];
;                 acc = __builtin_amdgcn_mfma_f32_16x16x32_bf16(bb, saf, acc, 0, 0, 0);
;                 acc = __builtin_amdgcn_mfma_f32_16x16x32_bf16(kb, vf, acc, 0, 0, 0);
	v_add_u32_e32 v164, s57, v7
	v_add_u32_e32 v158, s57, v161
	ds_read_b64_tr_b16 v[14:15], v164 offset:8192
	ds_read_b64_tr_b16 v[52:53], v164 offset:8704
	ds_read_b64_tr_b16 v[56:57], v164 offset:9728
	ds_read_b64_tr_b16 v[58:59], v164 offset:9216
	v_add_u32_e32 v168, s57, v166
	ds_read_b64_tr_b16 v[88:89], v158 offset:2048
	ds_read_b64_tr_b16 v[92:93], v158 offset:2056
	v_add_u32_e32 v82, s57, v159
	v_add_u32_e32 v156, s57, v13
	v_add_u32_e32 v157, s57, v160
	v_add_u32_e32 v167, s57, v165
	ds_read_b64_tr_b16 v[96:97], v168 offset:2048
	v_cvt_pk_bf16_f32 v28, v8, v9
	v_cvt_pk_bf16_f32 v29, v10, v11
	v_cvt_pk_bf16_f32 v30, v16, v17
	v_cvt_pk_bf16_f32 v31, v18, v19
	v_cvt_pk_bf16_f32 v32, v20, v21
	v_cvt_pk_bf16_f32 v33, v22, v23
	v_cvt_pk_bf16_f32 v34, v24, v25
	v_cvt_pk_bf16_f32 v35, v26, v27
	ds_read_b64_tr_b16 v[100:101], v168 offset:2056
	s_waitcnt lgkmcnt(12)
	v_mfma_f32_16x16x32_bf16 v[104:107], v[36:39], v[28:31], 0
	ds_read_b128 v[36:39], v82 offset:11520
	s_waitcnt lgkmcnt(12)
	v_mfma_f32_16x16x32_bf16 v[112:115], v[44:47], v[28:31], 0
	ds_read_b128 v[44:47], v82 offset:13568
	s_waitcnt lgkmcnt(12)
	v_mfma_f32_16x16x32_bf16 v[104:107], v[40:43], v[32:35], v[104:107]
	ds_read_b128 v[40:43], v167 offset:11520
	s_waitcnt lgkmcnt(12)
	v_mfma_f32_16x16x32_bf16 v[112:115], v[48:51], v[32:35], v[112:115]
	ds_read_b128 v[48:51], v167 offset:13568
	s_waitcnt lgkmcnt(11)
	s_nop 0
	v_mfma_f32_16x16x16_bf16 v[104:107], v[14:15], v[60:61], v[104:107]
	ds_read_b64_tr_b16 v[90:91], v158 offset:0
	ds_read_b64_tr_b16 v[94:95], v158 offset:8
	ds_read_b64_tr_b16 v[98:99], v168 offset:0
	ds_read_b64_tr_b16 v[102:103], v168 offset:8
	s_nop 3
	v_cvt_pk_bf16_f32 v54, v104, v105
	v_cvt_pk_bf16_f32 v55, v106, v107
	s_waitcnt lgkmcnt(14)
	s_nop 0
	v_mfma_f32_16x16x16_bf16 v[108:111], v[52:53], v[54:55], 0
	s_nop 7
	v_cvt_pk_bf16_f32 v62, v108, v109
	v_cvt_pk_bf16_f32 v63, v110, v111
	s_waitcnt lgkmcnt(0)
	s_nop 0
	v_mfma_f32_16x16x32_bf16 v[112:115], v[56:59], v[60:63], v[112:115]
	v_mfma_f32_16x16x32_bf16 v[8:11], v[88:91], v[60:63], v[8:11]
	v_mfma_f32_16x16x32_bf16 v[16:19], v[92:95], v[60:63], v[16:19]
	v_mfma_f32_16x16x32_bf16 v[20:23], v[96:99], v[60:63], v[20:23]
	v_mfma_f32_16x16x32_bf16 v[24:27], v[100:103], v[60:63], v[24:27]
	ds_read_b128 v[64:67], v157 offset:0
	ds_read_b128 v[68:71], v157 offset:16
	ds_read_b128 v[72:75], v157 offset:128
	ds_read_b128 v[84:87], v157 offset:144
	v_cvt_pk_bf16_f32 v163, v112, v112
	ds_read_b64 v[60:61], v156 offset:21760
	global_store_short v162, v163, s[48:49] offset:0
	v_cvt_pk_bf16_f32 v163, v113, v113
	global_store_short v162, v163, s[48:49] offset:1024
	v_cvt_pk_bf16_f32 v163, v114, v114
	global_store_short v162, v163, s[48:49] offset:2048
	v_cvt_pk_bf16_f32 v163, v115, v115
	global_store_short v162, v163, s[48:49] offset:3072
	s_waitcnt lgkmcnt(1)
	s_add_u32 s58, s58, 1
	s_add_u32 s48, s48, 0x4000
	s_addc_u32 s49, s49, 0
	v_pk_mul_f32 v[8:9], v[8:9], v[64:65]
	v_pk_mul_f32 v[10:11], v[10:11], v[66:67]
	v_pk_mul_f32 v[16:17], v[16:17], v[68:69]
	v_pk_mul_f32 v[18:19], v[18:19], v[70:71]
	v_pk_mul_f32 v[20:21], v[20:21], v[72:73]
	v_pk_mul_f32 v[22:23], v[22:23], v[74:75]
	v_pk_mul_f32 v[24:25], v[24:25], v[84:85]
	v_pk_mul_f32 v[26:27], v[26:27], v[86:87]
	s_add_u32 s57, s57, 11520
	s_cmp_ge_u32 s58, 256
	s_cbranch_scc1 .Lsc_c_itend
; __device__ __forceinline__ void phase_scan2(const Params& p, int l, LAS unsigned char* lds) {
;     ...
;         auto consume = [&](int c, LAS const unsigned char* sl) {
;             const bf16x8 s0 = __builtin_bit_cast(bf16x8, (u32x4){pk_bf16(ST[0][0], ST[0][1]), pk_bf16(ST[0][2], ST[0][3]), pk_bf16(ST[1][0], ST[1][1]), pk_bf16(ST[1][2], ST[1][3])});
;             const bf16x8 s1 = __builtin_bit_cast(bf16x8, (u32x4){pk_bf16(ST[2][0], ST[2][1]), pk_bf16(ST[2][2], ST[2][3]), pk_bf16(ST[3][0], ST[3][1]), pk_bf16(ST[3][2], ST[3][3])});
;             const bf16x8 at0 = *(LAS const bf16x8*)(sl + SC_AT + (fr * 32 + fq * 8) * 2), at1 = *(LAS const bf16x8*)(sl + SC_AT + ((16 + fr) * 32 + fq * 8) * 2);
;             const bf16x8 rt0 = *(LAS const bf16x8*)(sl + SC_RT + (fr * 32 + fq * 8) * 2), rt1 = *(LAS const bf16x8*)(sl + SC_RT + ((16 + fr) * 32 + fq * 8) * 2);
;             const int mo = (fr * 16 + 4 * fq) * 2;
;             const bf16x8 vf = frag4(sl + SC_VP + mo), akf = frag4(sl + SC_AK + mo), xf = frag4(sl + SC_X + mo), rbf = frag4(sl + SC_RB + mo), rkf = frag4(sl + SC_RK + mo);
;             const f32x4 z = (f32x4){0.f, 0.f, 0.f, 0.f};
;             f32x4 g = __builtin_amdgcn_mfma_f32_16x16x32_bf16(at0, s0, z, 0, 0, 0);
;             g = __builtin_amdgcn_mfma_f32_16x16x32_bf16(at1, s1, g, 0, 0, 0);
;             g = __builtin_amdgcn_mfma_f32_16x16x32_bf16(akf, vf, g, 0, 0, 0);
;             const f32x4 sa = __builtin_amdgcn_mfma_f32_16x16x32_bf16(xf, cfrag(g), z, 0, 0, 0);
;             const bf16x8 saf = cfrag(sa);
;             f32x4 y = __builtin_amdgcn_mfma_f32_16x16x32_bf16(rt0, s0, z, 0, 0, 0);
;             y = __builtin_amdgcn_mfma_f32_16x16x32_bf16(rt1, s1, y, 0, 0, 0);
;             y = __builtin_amdgcn_mfma_f32_16x16x32_bf16(rbf, saf, y, 0, 0, 0);
;             y = __builtin_amdgcn_mfma_f32_16x16x32_bf16(rkf, vf, y, 0, 0, 0);
; #pragma unroll
;             for (int jt = 0; jt < 4; ++jt) {
;                 const f32x4 wc = *(LAS const f32x4*)(sl + SC_WC + (16 * jt + 4 * fq) * 4);
;                 const bf16x8 bb = frag4(sl + SC_BBT + ((16 * jt + fr) * SC_BS + 4 * fq) * 2), kb = frag4(sl + SC_KBT + ((16 * jt + fr) * SC_BS + 4 * fq) * 2);
;                 f32x4 acc = ST[jt];
;                 acc = __builtin_amdgcn_mfma_f32_16x16x32_bf16(bb, saf, acc, 0, 0, 0);
;                 acc = __builtin_amdgcn_mfma_f32_16x16x32_bf16(kb, vf, acc, 0, 0, 0);
	v_add_u32_e32 v164, s57, v7
	v_add_u32_e32 v158, s57, v161
	ds_read_b64_tr_b16 v[14:15], v164 offset:8192
	ds_read_b64_tr_b16 v[52:53], v164 offset:8704
	ds_read_b64_tr_b16 v[56:57], v164 offset:9728
	ds_read_b64_tr_b16 v[58:59], v164 offset:9216
	v_add_u32_e32 v168, s57, v166
	ds_read_b64_tr_b16 v[88:89], v158 offset:2048
	ds_read_b64_tr_b16 v[92:93], v158 offset:2056
	v_add_u32_e32 v82, s57, v159
	v_add_u32_e32 v156, s57, v13
	v_add_u32_e32 v157, s57, v160
	v_add_u32_e32 v167, s57, v165
	ds_read_b64_tr_b16 v[96:97], v168 offset:2048
	v_cvt_pk_bf16_f32 v28, v8, v9
	v_cvt_pk_bf16_f32 v29, v10, v11
	v_cvt_pk_bf16_f32 v30, v16, v17
	v_cvt_pk_bf16_f32 v31, v18, v19
	v_cvt_pk_bf16_f32 v32, v20, v21
	v_cvt_pk_bf16_f32 v33, v22, v23
	v_cvt_pk_bf16_f32 v34, v24, v25
	v_cvt_pk_bf16_f32 v35, v26, v27
	ds_read_b64_tr_b16 v[100:101], v168 offset:2056
	s_waitcnt lgkmcnt(12)
	v_mfma_f32_16x16x32_bf16 v[104:107], v[36:39], v[28:31], 0
	ds_read_b128 v[36:39], v82 offset:11520
	s_waitcnt lgkmcnt(12)
	v_mfma_f32_16x16x32_bf16 v[112:115], v[44:47], v[28:31], 0
	ds_read_b128 v[44:47], v82 offset:13568
	s_waitcnt lgkmcnt(12)
	v_mfma_f32_16x16x32_bf16 v[104:107], v[40:43], v[32:35], v[104:107]
	ds_read_b128 v[40:43], v167 offset:11520
	s_waitcnt lgkmcnt(12)
	v_mfma_f32_16x16x32_bf16 v[112:115], v[48:51], v[32:35], v[112:115]
	ds_read_b128 v[48:51], v167 offset:13568
	s_waitcnt lgkmcnt(11)
	s_nop 0
	v_mfma_f32_16x16x16_bf16 v[104:107], v[14:15], v[60:61], v[104:107]
	ds_read_b64_tr_b16 v[90:91], v158 offset:0
	ds_read_b64_tr_b16 v[94:95], v158 offset:8
	ds_read_b64_tr_b16 v[98:99], v168 offset:0
	ds_read_b64_tr_b16 v[102:103], v168 offset:8
	s_nop 3
	v_cvt_pk_bf16_f32 v54, v104, v105
	v_cvt_pk_bf16_f32 v55, v106, v107
	s_waitcnt lgkmcnt(14)
	s_nop 0
	v_mfma_f32_16x16x16_bf16 v[108:111], v[52:53], v[54:55], 0
	s_nop 7
	v_cvt_pk_bf16_f32 v62, v108, v109
	v_cvt_pk_bf16_f32 v63, v110, v111
	s_waitcnt lgkmcnt(0)
	s_nop 0
	v_mfma_f32_16x16x32_bf16 v[112:115], v[56:59], v[60:63], v[112:115]
	v_mfma_f32_16x16x32_bf16 v[8:11], v[88:91], v[60:63], v[8:11]
	v_mfma_f32_16x16x32_bf16 v[16:19], v[92:95], v[60:63], v[16:19]
	v_mfma_f32_16x16x32_bf16 v[20:23], v[96:99], v[60:63], v[20:23]
	v_mfma_f32_16x16x32_bf16 v[24:27], v[100:103], v[60:63], v[24:27]
	ds_read_b128 v[64:67], v157 offset:0
	ds_read_b128 v[68:71], v157 offset:16
	ds_read_b128 v[72:75], v157 offset:128
	ds_read_b128 v[84:87], v157 offset:144
	v_cvt_pk_bf16_f32 v163, v112, v112
	ds_read_b64 v[60:61], v156 offset:21760
	global_store_short v162, v163, s[48:49] offset:0
	v_cvt_pk_bf16_f32 v163, v113, v113
	global_store_short v162, v163, s[48:49] offset:1024
	v_cvt_pk_bf16_f32 v163, v114, v114
	global_store_short v162, v163, s[48:49] offset:2048
	v_cvt_pk_bf16_f32 v163, v115, v115
	global_store_short v162, v163, s[48:49] offset:3072
	s_waitcnt lgkmcnt(1)
	s_add_u32 s58, s58, 1
	s_add_u32 s48, s48, 0x4000
	s_addc_u32 s49, s49, 0
	v_pk_mul_f32 v[8:9], v[8:9], v[64:65]
	v_pk_mul_f32 v[10:11], v[10:11], v[66:67]
	v_pk_mul_f32 v[16:17], v[16:17], v[68:69]
	v_pk_mul_f32 v[18:19], v[18:19], v[70:71]
	v_pk_mul_f32 v[20:21], v[20:21], v[72:73]
	v_pk_mul_f32 v[22:23], v[22:23], v[74:75]
	v_pk_mul_f32 v[24:25], v[24:25], v[84:85]
	v_pk_mul_f32 v[26:27], v[26:27], v[86:87]
	s_add_u32 s57, s57, 11520
	s_cmp_ge_u32 s58, 256
	s_cbranch_scc1 .Lsc_c_itend
	v_add_u32_e32 v164, s57, v7
	v_add_u32_e32 v158, s57, v161
	ds_read_b64_tr_b16 v[14:15], v164 offset:8192
	ds_read_b64_tr_b16 v[52:53], v164 offset:8704
	ds_read_b64_tr_b16 v[56:57], v164 offset:9728
	ds_read_b64_tr_b16 v[58:59], v164 offset:9216
	v_add_u32_e32 v168, s57, v166
	ds_read_b64_tr_b16 v[88:89], v158 offset:2048
	ds_read_b64_tr_b16 v[92:93], v158 offset:2056
	v_add_u32_e32 v82, s57, v159
	v_add_u32_e32 v156, s57, v13
	v_add_u32_e32 v157, s57, v160
	v_add_u32_e32 v167, s57, v165
	ds_read_b64_tr_b16 v[96:97], v168 offset:2048
	v_cvt_pk_bf16_f32 v28, v8, v9
	v_cvt_pk_bf16_f32 v29, v10, v11
	v_cvt_pk_bf16_f32 v30, v16, v17
	v_cvt_pk_bf16_f32 v31, v18, v19
	v_cvt_pk_bf16_f32 v32, v20, v21
	v_cvt_pk_bf16_f32 v33, v22, v23
	v_cvt_pk_bf16_f32 v34, v24, v25
	v_cvt_pk_bf16_f32 v35, v26, v27
	ds_read_b64_tr_b16 v[100:101], v168 offset:2056
	s_waitcnt lgkmcnt(12)
	v_mfma_f32_16x16x32_bf16 v[104:107], v[36:39], v[28:31], 0
	s_waitcnt lgkmcnt(11)
	v_mfma_f32_16x16x32_bf16 v[112:115], v[44:47], v[28:31], 0
	s_waitcnt lgkmcnt(10)
	v_mfma_f32_16x16x32_bf16 v[104:107], v[40:43], v[32:35], v[104:107]
	s_waitcnt lgkmcnt(9)
	v_mfma_f32_16x16x32_bf16 v[112:115], v[48:51], v[32:35], v[112:115]
	s_waitcnt lgkmcnt(7)
	s_nop 2
	v_mfma_f32_16x16x16_bf16 v[104:107], v[14:15], v[60:61], v[104:107]
	ds_read_b64_tr_b16 v[90:91], v158 offset:0
	ds_read_b64_tr_b16 v[94:95], v158 offset:8
	ds_read_b64_tr_b16 v[98:99], v168 offset:0
	ds_read_b64_tr_b16 v[102:103], v168 offset:8
	s_nop 3
	v_cvt_pk_bf16_f32 v54, v104, v105
	v_cvt_pk_bf16_f32 v55, v106, v107
	s_waitcnt lgkmcnt(10)
	s_nop 0
	v_mfma_f32_16x16x16_bf16 v[108:111], v[52:53], v[54:55], 0
	s_nop 7
	v_cvt_pk_bf16_f32 v62, v108, v109
	v_cvt_pk_bf16_f32 v63, v110, v111
	s_waitcnt lgkmcnt(0)
	s_nop 0
	v_mfma_f32_16x16x32_bf16 v[112:115], v[56:59], v[60:63], v[112:115]
	ds_read_b128 v[64:67], v157 offset:0
	ds_read_b128 v[68:71], v157 offset:16
	ds_read_b128 v[72:75], v157 offset:128
	ds_read_b128 v[84:87], v157 offset:144
	v_mfma_f32_16x16x32_bf16 v[8:11], v[88:91], v[60:63], v[8:11]
	v_mfma_f32_16x16x32_bf16 v[16:19], v[92:95], v[60:63], v[16:19]
	v_mfma_f32_16x16x32_bf16 v[20:23], v[96:99], v[60:63], v[20:23]
	v_mfma_f32_16x16x32_bf16 v[24:27], v[100:103], v[60:63], v[24:27]
	v_cvt_pk_bf16_f32 v163, v112, v112
	global_store_short v162, v163, s[48:49] offset:0
	v_cvt_pk_bf16_f32 v163, v113, v113
	global_store_short v162, v163, s[48:49] offset:1024
	v_cvt_pk_bf16_f32 v163, v114, v114
	global_store_short v162, v163, s[48:49] offset:2048
	v_cvt_pk_bf16_f32 v163, v115, v115
	global_store_short v162, v163, s[48:49] offset:3072
	s_waitcnt lgkmcnt(0)
	s_add_u32 s58, s58, 1
	s_add_u32 s48, s48, 0x4000
	v_pk_mul_f32 v[8:9], v[8:9], v[64:65]
	v_pk_mul_f32 v[10:11], v[10:11], v[66:67]
	v_pk_mul_f32 v[16:17], v[16:17], v[68:69]
	v_pk_mul_f32 v[18:19], v[18:19], v[70:71]
	v_pk_mul_f32 v[20:21], v[20:21], v[72:73]
	v_pk_mul_f32 v[22:23], v[22:23], v[74:75]
	v_pk_mul_f32 v[24:25], v[24:25], v[84:85]
	v_pk_mul_f32 v[26:27], v[26:27], v[86:87]
	s_addc_u32 s49, s49, 0
	s_add_u32 s57, s57, 11520
